# MODE3 epilogue read loops software-rotated: next iteration's six LDS tile reads issued at the end of the current iteration (latency hidden behind row/boundary bookkeeping)
# speedup vs baseline: 1.0091x; 1.0019x over previous
.LBB0_1152:
	v_and_b32_e32 v131, 0x7c, v129
	v_lshlrev_b32_e32 v129, 2, v131
	v_add_u32_e32 v141, s65, v129
	v_add_u32_e32 v142, s66, v129
	v_add_u32_e32 v143, s67, v129
	v_add_u32_e32 v144, s68, v129
	v_add_u32_e32 v145, s69, v129
	v_add_u32_e32 v146, s70, v129
	v_ashrrev_i32_e32 v129, 31, v128
	s_lshl_b64 s[18:19], s[20:21], 1
	v_lshl_add_u64 v[128:129], v[128:129], 1, s[14:15]
	v_lshlrev_b32_e32 v132, 1, v131
	v_mov_b32_e32 v133, v229
	v_ashrrev_i32_e32 v140, 5, v130
	s_add_u32 s18, s61, s18
	v_lshl_add_u64 v[136:137], v[128:129], 0, v[132:133]
	v_and_b32_e32 v129, 31, v130
	s_addc_u32 s19, s62, s19
	s_add_i32 s20, s25, s24
	v_mul_lo_u32 v128, v140, s71
	v_lshlrev_b32_e32 v129, 4, v129
	s_add_i32 s20, s20, s76
	v_add3_u32 v147, v128, v129, s72
	v_lshl_add_u64 v[138:139], s[18:19], 0, v[132:133]
	v_add_u32_e32 v165, s20, v140
	s_mov_b32 s21, 0
	v_mov_b32_e32 v166, v147
	s_waitcnt vmcnt(0) lgkmcnt(0)
	s_barrier
	ds_read_b128 v[184:187], v141
	ds_read_b128 v[188:191], v142
	ds_read_b128 v[192:195], v143
	ds_read_b128 v[196:199], v144
	ds_read_b128 v[200:203], v145
	ds_read_b128 v[204:207], v146
	ds_read_b128 v[132:135], v166 offset:1040
	ds_read_b128 v[128:131], v166 offset:1552
	ds_read_b128 v[208:211], v166
	ds_read_b128 v[212:215], v166 offset:512
	ds_read_b128 v[176:179], v166 offset:2080
	ds_read_b128 v[180:183], v166 offset:2592
	s_branch .LBB0_1154
.LBB0_1153:
	s_or_b64 exec, exec, s[18:19]
	s_add_i32 s21, s21, 16
	s_cmp_eq_u32 s21, 64
	v_add_u32_e32 v166, 0x4100, v166
	ds_read_b128 v[132:135], v166 offset:1040
	ds_read_b128 v[128:131], v166 offset:1552
	ds_read_b128 v[208:211], v166
	ds_read_b128 v[212:215], v166 offset:512
	ds_read_b128 v[176:179], v166 offset:2080
	ds_read_b128 v[180:183], v166 offset:2592
	s_cbranch_scc1 .LBB0_1158
.LBB0_1154:
	v_add_u32_e32 v168, s21, v140
	v_subrev_u32_e32 v169, 62, v168
	v_add_u32_e32 v167, s21, v165
	v_cmp_gt_u32_e32 vcc, s73, v169
	s_and_saveexec_b64 s[18:19], vcc
	s_cbranch_execz .LBB0_1156
	v_ashrrev_i32_e32 v169, 4, v167
	v_subrev_u32_e32 v170, 60, v168
	v_cmp_gt_i32_e32 vcc, 2, v168
	v_and_b32_e32 v169, -4, v169
	s_waitcnt lgkmcnt(5)
	v_cvt_pk_bf16_f32 v171, v134, v135
	v_cndmask_b32_e32 v170, v170, v168, vcc
	v_add_u32_e32 v169, v169, v170
	v_cvt_pk_bf16_f32 v170, v132, v133
	v_mad_i64_i32 v[172:173], s[22:23], v169, s74, v[138:139]
	global_store_dwordx2 v[172:173], v[170:171], off
	s_waitcnt lgkmcnt(4)
	v_cvt_pk_bf16_f32 v171, v130, v131
	v_cvt_pk_bf16_f32 v170, v128, v129
	global_store_dwordx2 v[172:173], v[170:171], off offset:256
.LBB0_1156:
	s_or_b64 exec, exec, s[18:19]
	v_add_u32_e32 v168, -1, v168
	v_cmp_gt_u32_e32 vcc, 62, v168
	s_and_saveexec_b64 s[18:19], vcc
	s_cbranch_execz .LBB0_1153
	s_waitcnt lgkmcnt(3)
	v_pk_mul_f32 v[134:135], v[134:135], v[190:191]
	v_pk_mul_f32 v[132:133], v[132:133], v[188:189]
	v_pk_fma_f32 v[134:135], v[210:211], v[186:187], v[134:135]
	v_pk_fma_f32 v[132:133], v[208:209], v[184:185], v[132:133]
	s_waitcnt lgkmcnt(1)
	v_pk_fma_f32 v[134:135], v[178:179], v[194:195], v[134:135]
	v_pk_fma_f32 v[132:133], v[176:177], v[192:193], v[132:133]
	v_mul_f32_e32 v170, 0xbfb8aa3b, v134
	v_mul_f32_e32 v168, 0xbfb8aa3b, v132
	v_mul_f32_e32 v169, 0xbfb8aa3b, v133
	v_mul_f32_e32 v171, 0xbfb8aa3b, v135
	v_exp_f32_e32 v168, v168
	v_exp_f32_e32 v169, v169
	v_exp_f32_e32 v170, v170
	v_exp_f32_e32 v171, v171
	v_add_f32_e32 v168, 1.0, v168
	v_add_f32_e32 v169, 1.0, v169
	v_add_f32_e32 v170, 1.0, v170
	v_add_f32_e32 v171, 1.0, v171
	v_rcp_f32_e32 v168, v168
	v_rcp_f32_e32 v169, v169
	v_rcp_f32_e32 v170, v170
	v_rcp_f32_e32 v171, v171
	s_waitcnt lgkmcnt(1)
	v_pk_mul_f32 v[130:131], v[130:131], v[202:203]
	v_pk_mul_f32 v[128:129], v[128:129], v[200:201]
	v_pk_fma_f32 v[130:131], v[214:215], v[198:199], v[130:131]
	v_pk_fma_f32 v[128:129], v[212:213], v[196:197], v[128:129]
	s_waitcnt lgkmcnt(0)
	v_pk_fma_f32 v[130:131], v[182:183], v[206:207], v[130:131]
	v_pk_fma_f32 v[128:129], v[180:181], v[204:205], v[128:129]
	v_pk_mul_f32 v[132:133], v[132:133], v[168:169]
	v_pk_mul_f32 v[134:135], v[134:135], v[170:171]
	v_pk_mul_f32 v[128:129], v[128:129], v[132:133]
	v_pk_mul_f32 v[130:131], v[130:131], v[134:135]
	s_nop 0
	v_cvt_pk_bf16_f32 v131, v130, v131
	v_cvt_pk_bf16_f32 v130, v128, v129
	v_mad_i64_i32 v[128:129], s[22:23], v167, s64, v[136:137]
	global_store_dwordx2 v[128:129], v[130:131], off
	s_branch .LBB0_1153

.LBB0_1160:
	v_add3_u32 v72, s20, 64, v140
	s_mov_b32 s21, 0
	v_mov_b32_e32 v73, v147
	s_waitcnt lgkmcnt(0)
	s_barrier
	ds_read_b128 v[68:71], v73 offset:1040
	ds_read_b128 v[64:67], v73 offset:1552
	ds_read_b128 v[92:95], v73
	ds_read_b128 v[96:99], v73 offset:512
	ds_read_b128 v[84:87], v73 offset:2080
	ds_read_b128 v[88:91], v73 offset:2592
	s_branch .LBB0_1162
.LBB0_1161:
	s_or_b64 exec, exec, s[18:19]
	s_add_i32 s21, s21, 16
	s_cmp_lg_u32 s21, 64
	v_add_u32_e32 v73, 0x4100, v73
	ds_read_b128 v[68:71], v73 offset:1040
	ds_read_b128 v[64:67], v73 offset:1552
	ds_read_b128 v[92:95], v73
	ds_read_b128 v[96:99], v73 offset:512
	ds_read_b128 v[84:87], v73 offset:2080
	ds_read_b128 v[88:91], v73 offset:2592
	s_cbranch_scc0 .LBB0_1166
.LBB0_1162:
	v_add_u32_e32 v75, s21, v140
	v_subrev_u32_e32 v76, 62, v75
	v_add_u32_e32 v74, s21, v72
	v_cmp_gt_u32_e32 vcc, s73, v76
	s_and_saveexec_b64 s[18:19], vcc
	s_cbranch_execz .LBB0_1164
	v_ashrrev_i32_e32 v76, 4, v74
	v_subrev_u32_e32 v77, 60, v75
	v_cmp_gt_i32_e32 vcc, 2, v75
	v_and_b32_e32 v76, -4, v76
	s_nop 0
	v_cndmask_b32_e32 v77, v77, v75, vcc
	v_add_u32_e32 v78, v76, v77
	s_waitcnt lgkmcnt(5)
	v_cvt_pk_bf16_f32 v77, v70, v71
	v_cvt_pk_bf16_f32 v76, v68, v69
	v_mad_i64_i32 v[78:79], s[22:23], v78, s74, v[138:139]
	global_store_dwordx2 v[78:79], v[76:77], off
	s_waitcnt lgkmcnt(4)
	v_cvt_pk_bf16_f32 v77, v66, v67
	v_cvt_pk_bf16_f32 v76, v64, v65
	global_store_dwordx2 v[78:79], v[76:77], off offset:256
.LBB0_1164:
	s_or_b64 exec, exec, s[18:19]
	v_add_u32_e32 v75, -1, v75
	v_cmp_gt_u32_e32 vcc, 62, v75
	s_and_saveexec_b64 s[18:19], vcc
	s_cbranch_execz .LBB0_1161
	s_waitcnt lgkmcnt(3)
	v_pk_mul_f32 v[68:69], v[68:69], v[188:189]
	v_pk_mul_f32 v[70:71], v[70:71], v[190:191]
	v_pk_fma_f32 v[68:69], v[92:93], v[184:185], v[68:69]
	v_pk_fma_f32 v[70:71], v[94:95], v[186:187], v[70:71]
	s_waitcnt lgkmcnt(1)
	v_pk_fma_f32 v[68:69], v[84:85], v[192:193], v[68:69]
	v_pk_fma_f32 v[70:71], v[86:87], v[194:195], v[70:71]
	v_mul_f32_e32 v75, 0xbfb8aa3b, v68
	v_exp_f32_e32 v75, v75
	v_mul_f32_e32 v76, 0xbfb8aa3b, v69
	v_exp_f32_e32 v77, v76
	s_waitcnt lgkmcnt(1)
	v_pk_mul_f32 v[66:67], v[66:67], v[202:203]
	v_add_f32_e32 v75, 1.0, v75
	v_rcp_f32_e32 v76, v75
	v_add_f32_e32 v75, 1.0, v77
	v_mul_f32_e32 v77, 0xbfb8aa3b, v70
	v_exp_f32_e32 v78, v77
	v_mul_f32_e32 v77, 0xbfb8aa3b, v71
	v_exp_f32_e32 v79, v77
	v_rcp_f32_e32 v77, v75
	v_add_f32_e32 v75, 1.0, v78
	v_rcp_f32_e32 v78, v75
	v_add_f32_e32 v75, 1.0, v79
	v_rcp_f32_e32 v79, v75
	v_pk_mul_f32 v[64:65], v[64:65], v[200:201]
	v_pk_fma_f32 v[66:67], v[98:99], v[198:199], v[66:67]
	v_pk_fma_f32 v[64:65], v[96:97], v[196:197], v[64:65]
	s_waitcnt lgkmcnt(0)
	v_pk_fma_f32 v[66:67], v[90:91], v[206:207], v[66:67]
	v_pk_fma_f32 v[64:65], v[88:89], v[204:205], v[64:65]
	v_pk_mul_f32 v[68:69], v[68:69], v[76:77]
	v_pk_mul_f32 v[70:71], v[70:71], v[78:79]
	v_pk_mul_f32 v[64:65], v[64:65], v[68:69]
	v_pk_mul_f32 v[66:67], v[66:67], v[70:71]
	s_nop 0
	v_cvt_pk_bf16_f32 v67, v66, v67
	v_cvt_pk_bf16_f32 v66, v64, v65
	v_mad_i64_i32 v[64:65], s[22:23], v74, s64, v[136:137]
	global_store_dwordx2 v[64:65], v[66:67], off
	s_branch .LBB0_1161

.LBB0_1169:
	s_add_i32 s4, s20, 0x80
	v_add_u32_e32 v72, s4, v140
	s_mov_b32 s6, 0
	v_mov_b32_e32 v73, v147
	s_waitcnt lgkmcnt(0)
	s_barrier
	ds_read_b128 v[68:71], v73 offset:1040
	ds_read_b128 v[64:67], v73 offset:1552
	ds_read_b128 v[92:95], v73
	ds_read_b128 v[96:99], v73 offset:512
	ds_read_b128 v[84:87], v73 offset:2080
	ds_read_b128 v[88:91], v73 offset:2592
	s_branch .LBB0_1171
.LBB0_1170:
	s_or_b64 exec, exec, s[4:5]
	s_add_i32 s6, s6, 16
	s_cmp_lg_u32 s6, 64
	v_add_u32_e32 v73, 0x4100, v73
	ds_read_b128 v[68:71], v73 offset:1040
	ds_read_b128 v[64:67], v73 offset:1552
	ds_read_b128 v[92:95], v73
	ds_read_b128 v[96:99], v73 offset:512
	ds_read_b128 v[84:87], v73 offset:2080
	ds_read_b128 v[88:91], v73 offset:2592
	s_cbranch_scc0 .LBB0_1175
.LBB0_1171:
	v_add_u32_e32 v75, s6, v140
	v_subrev_u32_e32 v76, 62, v75
	v_add_u32_e32 v74, s6, v72
	v_cmp_gt_u32_e32 vcc, s73, v76
	s_and_saveexec_b64 s[4:5], vcc
	s_cbranch_execz .LBB0_1173
	v_ashrrev_i32_e32 v76, 4, v74
	v_subrev_u32_e32 v77, 60, v75
	v_cmp_gt_i32_e32 vcc, 2, v75
	v_and_b32_e32 v76, -4, v76
	s_nop 0
	v_cndmask_b32_e32 v77, v77, v75, vcc
	v_add_u32_e32 v78, v76, v77
	s_waitcnt lgkmcnt(5)
	v_cvt_pk_bf16_f32 v77, v70, v71
	v_cvt_pk_bf16_f32 v76, v68, v69
	v_mad_i64_i32 v[78:79], s[18:19], v78, s74, v[138:139]
	global_store_dwordx2 v[78:79], v[76:77], off
	s_waitcnt lgkmcnt(4)
	v_cvt_pk_bf16_f32 v77, v66, v67
	v_cvt_pk_bf16_f32 v76, v64, v65
	global_store_dwordx2 v[78:79], v[76:77], off offset:256
.LBB0_1173:
	s_or_b64 exec, exec, s[4:5]
	v_add_u32_e32 v75, -1, v75
	v_cmp_gt_u32_e32 vcc, 62, v75
	s_and_saveexec_b64 s[4:5], vcc
	s_cbranch_execz .LBB0_1170
	s_waitcnt lgkmcnt(3)
	v_pk_mul_f32 v[68:69], v[68:69], v[188:189]
	v_pk_mul_f32 v[70:71], v[70:71], v[190:191]
	v_pk_fma_f32 v[68:69], v[92:93], v[184:185], v[68:69]
	v_pk_fma_f32 v[70:71], v[94:95], v[186:187], v[70:71]
	s_waitcnt lgkmcnt(1)
	v_pk_fma_f32 v[68:69], v[84:85], v[192:193], v[68:69]
	v_pk_fma_f32 v[70:71], v[86:87], v[194:195], v[70:71]
	v_mul_f32_e32 v75, 0xbfb8aa3b, v68
	v_exp_f32_e32 v75, v75
	v_mul_f32_e32 v76, 0xbfb8aa3b, v69
	v_exp_f32_e32 v77, v76
	s_waitcnt lgkmcnt(1)
	v_pk_mul_f32 v[66:67], v[66:67], v[202:203]
	v_add_f32_e32 v75, 1.0, v75
	v_rcp_f32_e32 v76, v75
	v_add_f32_e32 v75, 1.0, v77
	v_mul_f32_e32 v77, 0xbfb8aa3b, v70
	v_exp_f32_e32 v78, v77
	v_mul_f32_e32 v77, 0xbfb8aa3b, v71
	v_exp_f32_e32 v79, v77
	v_rcp_f32_e32 v77, v75
	v_add_f32_e32 v75, 1.0, v78
	v_rcp_f32_e32 v78, v75
	v_add_f32_e32 v75, 1.0, v79
	v_rcp_f32_e32 v79, v75
	v_pk_mul_f32 v[64:65], v[64:65], v[200:201]
	v_pk_fma_f32 v[66:67], v[98:99], v[198:199], v[66:67]
	v_pk_fma_f32 v[64:65], v[96:97], v[196:197], v[64:65]
	s_waitcnt lgkmcnt(0)
	v_pk_fma_f32 v[66:67], v[90:91], v[206:207], v[66:67]
	v_pk_fma_f32 v[64:65], v[88:89], v[204:205], v[64:65]
	v_pk_mul_f32 v[68:69], v[68:69], v[76:77]
	v_pk_mul_f32 v[70:71], v[70:71], v[78:79]
	v_pk_mul_f32 v[64:65], v[64:65], v[68:69]
	v_pk_mul_f32 v[66:67], v[66:67], v[70:71]
	s_nop 0
	v_cvt_pk_bf16_f32 v67, v66, v67
	v_cvt_pk_bf16_f32 v66, v64, v65
	v_mad_i64_i32 v[64:65], s[18:19], v74, s64, v[136:137]
	global_store_dwordx2 v[64:65], v[66:67], off
	s_branch .LBB0_1170

.LBB0_1177:
	s_addk_i32 s20, 0xc0
	v_add_u32_e32 v8, s20, v140
	s_mov_b32 s4, 0
	s_waitcnt lgkmcnt(0)
	s_barrier
	ds_read_b128 v[4:7], v147 offset:1040
	ds_read_b128 v[0:3], v147 offset:1552
	ds_read_b128 v[26:29], v147
	ds_read_b128 v[30:33], v147 offset:512
	ds_read_b128 v[18:21], v147 offset:2080
	ds_read_b128 v[22:25], v147 offset:2592
	s_branch .LBB0_1179
.LBB0_1178:
	s_or_b64 exec, exec, s[2:3]
	s_add_i32 s4, s4, 16
	s_cmp_lg_u32 s4, 64
	v_add_u32_e32 v147, 0x4100, v147
	ds_read_b128 v[4:7], v147 offset:1040
	ds_read_b128 v[0:3], v147 offset:1552
	ds_read_b128 v[26:29], v147
	ds_read_b128 v[30:33], v147 offset:512
	ds_read_b128 v[18:21], v147 offset:2080
	ds_read_b128 v[22:25], v147 offset:2592
	s_cbranch_scc0 .LBB0_1118
.LBB0_1179:
	v_add_u32_e32 v10, s4, v140
	v_subrev_u32_e32 v11, 62, v10
	v_add_u32_e32 v9, s4, v8
	v_cmp_gt_u32_e32 vcc, s73, v11
	s_and_saveexec_b64 s[2:3], vcc
	s_cbranch_execz .LBB0_1181
	v_ashrrev_i32_e32 v11, 4, v9
	v_subrev_u32_e32 v12, 60, v10
	v_cmp_gt_i32_e32 vcc, 2, v10
	v_and_b32_e32 v11, -4, v11
	s_waitcnt lgkmcnt(5)
	v_cvt_pk_bf16_f32 v13, v6, v7
	v_cndmask_b32_e32 v12, v12, v10, vcc
	v_add_u32_e32 v11, v11, v12
	v_cvt_pk_bf16_f32 v12, v4, v5
	v_mad_i64_i32 v[14:15], s[6:7], v11, s74, v[138:139]
	global_store_dwordx2 v[14:15], v[12:13], off
	s_waitcnt lgkmcnt(4)
	v_cvt_pk_bf16_f32 v13, v2, v3
	v_cvt_pk_bf16_f32 v12, v0, v1
	global_store_dwordx2 v[14:15], v[12:13], off offset:256
.LBB0_1181:
	s_or_b64 exec, exec, s[2:3]
	v_add_u32_e32 v10, -1, v10
	v_cmp_gt_u32_e32 vcc, 62, v10
	s_and_saveexec_b64 s[2:3], vcc
	s_cbranch_execz .LBB0_1178
	s_waitcnt lgkmcnt(3)
	v_pk_mul_f32 v[6:7], v[6:7], v[190:191]
	v_pk_mul_f32 v[4:5], v[4:5], v[188:189]
	v_pk_fma_f32 v[6:7], v[28:29], v[186:187], v[6:7]
	v_pk_fma_f32 v[4:5], v[26:27], v[184:185], v[4:5]
	s_waitcnt lgkmcnt(1)
	v_pk_fma_f32 v[6:7], v[20:21], v[194:195], v[6:7]
	v_pk_fma_f32 v[4:5], v[18:19], v[192:193], v[4:5]
	v_mul_f32_e32 v12, 0xbfb8aa3b, v6
	v_mul_f32_e32 v10, 0xbfb8aa3b, v4
	v_mul_f32_e32 v11, 0xbfb8aa3b, v5
	v_mul_f32_e32 v13, 0xbfb8aa3b, v7
	v_exp_f32_e32 v10, v10
	v_exp_f32_e32 v11, v11
	v_exp_f32_e32 v12, v12
	v_exp_f32_e32 v13, v13
	v_add_f32_e32 v10, 1.0, v10
	v_add_f32_e32 v11, 1.0, v11
	v_add_f32_e32 v12, 1.0, v12
	v_add_f32_e32 v13, 1.0, v13
	v_rcp_f32_e32 v10, v10
	v_rcp_f32_e32 v11, v11
	v_rcp_f32_e32 v12, v12
	v_rcp_f32_e32 v13, v13
	s_waitcnt lgkmcnt(1)
	v_pk_mul_f32 v[2:3], v[2:3], v[202:203]
	v_pk_mul_f32 v[0:1], v[0:1], v[200:201]
	v_pk_fma_f32 v[2:3], v[32:33], v[198:199], v[2:3]
	v_pk_fma_f32 v[0:1], v[30:31], v[196:197], v[0:1]
	s_waitcnt lgkmcnt(0)
	v_pk_fma_f32 v[2:3], v[24:25], v[206:207], v[2:3]
	v_pk_fma_f32 v[0:1], v[22:23], v[204:205], v[0:1]
	v_pk_mul_f32 v[4:5], v[4:5], v[10:11]
	v_pk_mul_f32 v[6:7], v[6:7], v[12:13]
	v_pk_mul_f32 v[0:1], v[0:1], v[4:5]
	v_pk_mul_f32 v[2:3], v[2:3], v[6:7]
	s_nop 0
	v_cvt_pk_bf16_f32 v3, v2, v3
	v_cvt_pk_bf16_f32 v2, v0, v1
	v_mad_i64_i32 v[0:1], s[6:7], v9, s64, v[136:137]
	global_store_dwordx2 v[0:1], v[2:3], off
	s_branch .LBB0_1178
